# v8 + the six GEMM K-loop heads aligned to 64 bytes (.p2align 6): code placement only
# speedup vs baseline: 1.1227x; 1.0036x over previous
;     __device__ __forceinline__ bool next(int i, Unit& u) const {
;         const bool hm = c < nmini, mini = hm && i == 0;
;         int j = i - (hm ? 1 : 0); j = j < 0 ? 0 : j;
;         const int ip = j >> pair;
;         const bool sk = skew > 0 && ip >= nfull;
;         const long L = sk ? (long)nfull * G + (long)(ip - nfull) * (G - skew) + (c - skew) : (long)ip * G + c; const bool ok = L < nwg && (!sk || c >= skew);
;         int wgid = ok ? (int)L : 0; { const int q = nwg / NXCD, r = nwg % NXCD, xcd = wgid % NXCD, off = wgid / NXCD; wgid = (xcd < r ? xcd * (q + 1) : r * (q + 1) + (xcd - r) * q) + off; }
;         const int nig = WGM * nN, gid = wgid / nig, fm = gid * WGM, gsz = (nM - fm) < WGM ? (nM - fm) : WGM;
;         const int fpm = fm + ((wgid % nig) % gsz), fpn = (wgid % nig) / gsz;
;         const int ns = nsplit > 0 ? nsplit : 1, t = c / ns, ks = c - t * ns, mpm = mini_pm0 + t / nN, mpn = t % nN;
;         u.pm = __builtin_amdgcn_readfirstlane(mini ? mpm : fpm); u.pn = __builtin_amdgcn_readfirstlane(mini ? mpn : fpn);
; template <class Epi, bool ALIGN_EPI = true, bool FP8 = false>
; __device__ __forceinline__ void gemm_phase(LAS unsigned char* lds, const Gemm g, const StaticOrder& S, const Epi& E, const int wid) {
;     ...
; #pragma unroll
;         for (int a = 0; a < 2; ++a)
; #pragma unroll
;             for (int b = 0; b < 2; ++b)
; #pragma unroll
;                 for (int m = 0; m < 4; ++m) {
;                     if (!keep) { acc[a][b][m][0] = (f32x4){0.f, 0.f, 0.f, 0.f}; acc[a][b][m][1] = (f32x4){0.f, 0.f, 0.f, 0.f}; }
;                     if constexpr (FP8) acc8[a][b][m] = __builtin_shufflevector(acc[a][b][m][0], acc[a][b][m][1], 0, 1, 2, 3, 4, 5, 6, 7); }
.LBB0_504:
	s_add_i32 s90, s90, 1
	s_add_i32 s3, s90, s49
	s_mul_i32 s6, s3, s50
	s_mul_hi_u32 s7, s3, s33
	s_add_i32 s7, s7, s6
	s_mul_i32 s3, s3, s33
	s_add_u32 s22, s3, s2
	s_addc_u32 s23, s7, s49
	v_cmp_lt_i64_e64 s[6:7], s[22:23], v[144:145]
	s_and_b64 s[24:25], s[6:7], exec
	s_cselect_b32 s3, s22, 0
	s_ashr_i32 s22, s3, 31
	s_lshr_b32 s22, s22, 29
	s_add_i32 s22, s3, s22
	s_ashr_i32 s23, s22, 3
	s_and_b32 s22, s22, -8
	s_sub_i32 s3, s3, s22
	s_cmp_lt_i32 s3, 0
	s_cselect_b32 s22, s85, 0x104
	s_mul_i32 s3, s3, s22
	s_add_i32 s3, s3, s23
	s_ashr_i32 s22, s3, 31
	s_lshr_b32 s22, s22, 26
	s_add_i32 s22, s3, s22
	s_ashr_i32 s23, s22, 6
	s_lshl_b32 s23, s23, 2
	s_sub_i32 s24, 0x82, s23
	s_min_i32 s24, s24, 4
	s_abs_i32 s25, s24
	v_cvt_f32_u32_e32 v0, s25
	s_sub_i32 s27, 0, s25
	s_andn2_b32 s22, s22, 63
	s_sub_i32 s3, s3, s22
	v_rcp_iflag_f32_e32 v0, v0
	s_abs_i32 s22, s3
	s_xor_b32 s26, s3, s24
	s_ashr_i32 s26, s26, 31
	v_mul_f32_e32 v0, 0x4f7ffffe, v0
	v_cvt_u32_f32_e32 v0, v0
	s_nop 0
	v_readfirstlane_b32 s28, v0
	s_mul_i32 s27, s27, s28
	s_mul_hi_u32 s27, s28, s27
	s_add_i32 s28, s28, s27
	s_mul_hi_u32 s27, s22, s28
	s_mul_i32 s28, s27, s25
	s_sub_i32 s22, s22, s28
	s_add_i32 s28, s27, 1
	s_sub_i32 s29, s22, s25
	s_cmp_ge_u32 s22, s25
	s_cselect_b32 s27, s28, s27
	s_cselect_b32 s22, s29, s22
	s_add_i32 s28, s27, 1
	s_cmp_ge_u32 s22, s25
	s_cselect_b32 s22, s28, s27
	s_xor_b32 s22, s22, s26
	s_sub_i32 s25, s22, s26
	s_mul_i32 s22, s25, s24
	s_sub_i32 s3, s3, s22
	s_add_i32 s22, s23, s3
	s_cmp_gt_i32 s25, 7
	s_cselect_b32 s3, 4, 0
	s_add_i32 s3, s25, s3
	s_ashr_i32 s23, s22, 31
	s_add_i32 s24, s3, 4
	s_lshl_b64 s[26:27], s[22:23], 20
	s_add_u32 s26, s56, s26
	s_addc_u32 s27, s57, s27
	s_ashr_i32 s25, s24, 31
	s_lshl_b64 s[28:29], s[24:25], 20
	s_add_u32 s28, s53, s28
	s_addc_u32 s29, s55, s29
	s_cmp_eq_u32 s9, 0
	s_cbranch_scc1 .LBB0_558
	s_and_b64 s[36:37], s[6:7], exec
	s_cselect_b32 s3, s27, s31
	s_cselect_b32 s23, s26, s30
	s_cselect_b32 s25, s29, s35
	s_cselect_b32 s38, s28, s34
	s_add_i32 s39, s9, -2
	s_add_u32 s30, s30, 0x80080
	s_addc_u32 s31, s31, 0
	s_add_u32 s42, s34, 0x100
	v_mov_b32_e32 v0, 0
	s_addc_u32 s43, s35, 0
	s_mov_b32 s34, 0
	v_mov_b32_e32 v1, v0
	v_mov_b32_e32 v2, v0
	v_mov_b32_e32 v3, v0
	v_mov_b32_e32 v4, v0
	v_mov_b32_e32 v5, v0
	v_mov_b32_e32 v6, v0
	v_mov_b32_e32 v7, v0
	v_mov_b32_e32 v16, v0
	v_mov_b32_e32 v17, v0
	v_mov_b32_e32 v18, v0
	v_mov_b32_e32 v19, v0
	v_mov_b32_e32 v20, v0
	v_mov_b32_e32 v21, v0
	v_mov_b32_e32 v22, v0
	v_mov_b32_e32 v23, v0
	v_mov_b32_e32 v32, v0
	s_waitcnt lgkmcnt(0)
	v_mov_b32_e32 v33, v0
	v_mov_b32_e32 v34, v0
	v_mov_b32_e32 v35, v0
	v_mov_b32_e32 v36, v0
	v_mov_b32_e32 v37, v0
	v_mov_b32_e32 v38, v0
	v_mov_b32_e32 v39, v0
	v_mov_b32_e32 v48, v0
	v_mov_b32_e32 v49, v0
	v_mov_b32_e32 v50, v0
	v_mov_b32_e32 v51, v0
	v_mov_b32_e32 v52, v0
	v_mov_b32_e32 v53, v0
	v_mov_b32_e32 v54, v0
	v_mov_b32_e32 v55, v0
	v_mov_b32_e32 v8, v0
	v_mov_b32_e32 v9, v0
	v_mov_b32_e32 v10, v0
	v_mov_b32_e32 v11, v0
	v_mov_b32_e32 v12, v0
	v_mov_b32_e32 v13, v0
	v_mov_b32_e32 v14, v0
	v_mov_b32_e32 v15, v0
	v_mov_b32_e32 v24, v0
	v_mov_b32_e32 v25, v0
	v_mov_b32_e32 v26, v0
	v_mov_b32_e32 v27, v0
	v_mov_b32_e32 v28, v0
	v_mov_b32_e32 v29, v0
	v_mov_b32_e32 v30, v0
	v_mov_b32_e32 v31, v0
	v_mov_b32_e32 v40, v0
	v_mov_b32_e32 v41, v0
	v_mov_b32_e32 v42, v0
	v_mov_b32_e32 v43, v0
	v_mov_b32_e32 v44, v0
	v_mov_b32_e32 v45, v0
	v_mov_b32_e32 v46, v0
	v_mov_b32_e32 v47, v0
	v_mov_b32_e32 v56, v0
	v_mov_b32_e32 v57, v0
	v_mov_b32_e32 v58, v0
	v_mov_b32_e32 v59, v0
	v_mov_b32_e32 v60, v0
	v_mov_b32_e32 v61, v0
	v_mov_b32_e32 v62, v0
	v_mov_b32_e32 v63, v0
	v_mov_b32_e32 v64, v0
	v_mov_b32_e32 v65, v0
	v_mov_b32_e32 v66, v0
	v_mov_b32_e32 v67, v0
	v_mov_b32_e32 v68, v0
	v_mov_b32_e32 v69, v0
	v_mov_b32_e32 v70, v0
	v_mov_b32_e32 v71, v0
	v_mov_b32_e32 v80, v0
	v_mov_b32_e32 v81, v0
	v_mov_b32_e32 v82, v0
	v_mov_b32_e32 v83, v0
	v_mov_b32_e32 v84, v0
	v_mov_b32_e32 v85, v0
	v_mov_b32_e32 v86, v0
	v_mov_b32_e32 v87, v0
	v_mov_b32_e32 v96, v0
	v_mov_b32_e32 v97, v0
	v_mov_b32_e32 v98, v0
	v_mov_b32_e32 v99, v0
	v_mov_b32_e32 v100, v0
	v_mov_b32_e32 v101, v0
	v_mov_b32_e32 v102, v0
	v_mov_b32_e32 v103, v0
	v_mov_b32_e32 v112, v0
	v_mov_b32_e32 v113, v0
	v_mov_b32_e32 v114, v0
	v_mov_b32_e32 v115, v0
	v_mov_b32_e32 v116, v0
	v_mov_b32_e32 v117, v0
	v_mov_b32_e32 v118, v0
	v_mov_b32_e32 v119, v0
	v_mov_b32_e32 v72, v0
	v_mov_b32_e32 v73, v0
	v_mov_b32_e32 v74, v0
	v_mov_b32_e32 v75, v0
	v_mov_b32_e32 v76, v0
	v_mov_b32_e32 v77, v0
	v_mov_b32_e32 v78, v0
	v_mov_b32_e32 v79, v0
	v_mov_b32_e32 v88, v0
	v_mov_b32_e32 v89, v0
	v_mov_b32_e32 v90, v0
	v_mov_b32_e32 v91, v0
	v_mov_b32_e32 v92, v0
	v_mov_b32_e32 v93, v0
	v_mov_b32_e32 v94, v0
	v_mov_b32_e32 v95, v0
	v_mov_b32_e32 v104, v0
	v_mov_b32_e32 v105, v0
	v_mov_b32_e32 v106, v0
	v_mov_b32_e32 v107, v0
	v_mov_b32_e32 v108, v0
	v_mov_b32_e32 v109, v0
	v_mov_b32_e32 v110, v0
	v_mov_b32_e32 v111, v0
	v_mov_b32_e32 v120, v0
	v_mov_b32_e32 v121, v0
	v_mov_b32_e32 v122, v0
	v_mov_b32_e32 v123, v0
	v_mov_b32_e32 v124, v0
	v_mov_b32_e32 v125, v0
	v_mov_b32_e32 v126, v0
	v_mov_b32_e32 v127, v0
	.p2align	6

;     __device__ __forceinline__ bool next(int i, Unit& u) const {
;         const bool hm = c < nmini, mini = hm && i == 0;
;         int j = i - (hm ? 1 : 0); j = j < 0 ? 0 : j;
;         const int ip = j >> pair;
;         const bool sk = skew > 0 && ip >= nfull;
;         const long L = sk ? (long)nfull * G + (long)(ip - nfull) * (G - skew) + (c - skew) : (long)ip * G + c; const bool ok = L < nwg && (!sk || c >= skew);
;         int wgid = ok ? (int)L : 0; { const int q = nwg / NXCD, r = nwg % NXCD, xcd = wgid % NXCD, off = wgid / NXCD; wgid = (xcd < r ? xcd * (q + 1) : r * (q + 1) + (xcd - r) * q) + off; }
;         const int nig = WGM * nN, gid = wgid / nig, fm = gid * WGM, gsz = (nM - fm) < WGM ? (nM - fm) : WGM;
;         const int fpm = fm + ((wgid % nig) % gsz), fpn = (wgid % nig) / gsz;
;         const int ns = nsplit > 0 ? nsplit : 1, t = c / ns, ks = c - t * ns, mpm = mini_pm0 + t / nN, mpn = t % nN;
;         u.pm = __builtin_amdgcn_readfirstlane(mini ? mpm : fpm); u.pn = __builtin_amdgcn_readfirstlane(mini ? mpn : fpn);
; template <class Epi, bool ALIGN_EPI = true, bool FP8 = false>
; __device__ __forceinline__ void gemm_phase(LAS unsigned char* lds, const Gemm g, const StaticOrder& S, const Epi& E, const int wid) {
;     ...
; #pragma unroll
;         for (int a = 0; a < 2; ++a)
; #pragma unroll
;             for (int b = 0; b < 2; ++b)
; #pragma unroll
;                 for (int m = 0; m < 4; ++m) {
;                     if (!keep) { acc[a][b][m][0] = (f32x4){0.f, 0.f, 0.f, 0.f}; acc[a][b][m][1] = (f32x4){0.f, 0.f, 0.f, 0.f}; }
;                     if constexpr (FP8) acc8[a][b][m] = __builtin_shufflevector(acc[a][b][m][0], acc[a][b][m][1], 0, 1, 2, 3, 4, 5, 6, 7); }
.LBB0_570:
	v_cmp_gt_i64_e32 vcc, s[20:21], v[176:177]
	s_or_b64 s[16:17], s[16:17], vcc
	v_cmp_lt_i64_e32 vcc, s[20:21], v[174:175]
	s_and_b64 s[16:17], s[16:17], exec
	v_readfirstlane_b32 s16, v189
	v_cndmask_b32_e64 v0, 0, 1, vcc
	s_nop 0
	v_readfirstlane_b32 s3, v0
	s_cselect_b32 s3, s3, s16
	s_bitcmp1_b32 s3, 0
	s_cselect_b64 s[16:17], -1, 0
	s_and_b64 s[22:23], s[16:17], exec
	s_cselect_b32 s3, s20, 0
	s_ashr_i32 s20, s3, 31
	s_lshr_b32 s20, s20, 29
	s_add_i32 s20, s3, s20
	s_ashr_i32 s21, s20, 3
	s_and_b32 s20, s20, -8
	s_sub_i32 s3, s3, s20
	s_cmp_lt_i32 s3, 0
	s_cselect_b32 s20, s74, 0x186
	s_mul_i32 s3, s3, s20
	s_add_i32 s3, s3, s21
	s_mul_hi_i32 s20, s3, 0x2aaaaaab
	s_lshr_b32 s21, s20, 31
	s_ashr_i32 s20, s20, 4
	s_add_i32 s20, s20, s21
	s_lshl_b32 s21, s20, 2
	s_sub_i32 s22, 0x82, s21
	s_min_i32 s22, s22, 4
	s_abs_i32 s23, s22
	v_cvt_f32_u32_e32 v0, s23
	s_sub_i32 s25, 0, s23
	s_mulk_i32 s20, 0x60
	s_sub_i32 s3, s3, s20
	v_rcp_iflag_f32_e32 v0, v0
	s_abs_i32 s24, s3
	s_xor_b32 s20, s3, s22
	s_ashr_i32 s20, s20, 31
	v_mul_f32_e32 v0, 0x4f7ffffe, v0
	v_cvt_u32_f32_e32 v0, v0
	s_nop 0
	v_readfirstlane_b32 s28, v0
	s_mul_i32 s25, s25, s28
	s_mul_hi_u32 s25, s28, s25
	s_add_i32 s28, s28, s25
	s_mul_hi_u32 s25, s24, s28
	s_mul_i32 s28, s25, s23
	s_sub_i32 s24, s24, s28
	s_add_i32 s28, s25, 1
	s_sub_i32 s29, s24, s23
	s_cmp_ge_u32 s24, s23
	s_cselect_b32 s25, s28, s25
	s_cselect_b32 s24, s29, s24
	s_add_i32 s28, s25, 1
	s_cmp_ge_u32 s24, s23
	s_cselect_b32 s23, s28, s25
	s_xor_b32 s23, s23, s20
	s_sub_i32 s23, s23, s20
	s_mul_i32 s20, s23, s22
	s_sub_i32 s3, s3, s20
	s_add_i32 s20, s21, s3
	s_cmp_gt_i32 s23, 3
	s_cselect_b32 s3, 8, 0
	s_add_i32 s3, s3, s23
	s_cmp_lt_i32 s23, 8
	s_cselect_b32 s21, 0, 8
	s_add_i32 s22, s3, s21
	s_ashr_i32 s21, s20, 31
	s_lshl_b64 s[24:25], s[20:21], 19
	s_add_u32 s24, s38, s24
	s_addc_u32 s25, s39, s25
	s_ashr_i32 s23, s22, 31
	s_lshl_b64 s[28:29], s[22:23], 19
	s_add_u32 s28, s51, s28
	s_addc_u32 s29, s53, s29
	s_cmp_eq_u32 s83, 0
	s_cbranch_scc1 .LBB0_582
	s_and_b64 s[36:37], s[16:17], exec
	s_cselect_b32 s21, s25, s31
	s_cselect_b32 s23, s24, s30
	s_cselect_b32 s84, s29, s35
	s_cselect_b32 s85, s28, s34
	s_add_i32 s86, s83, -2
	s_add_u32 s30, s30, 0x40080
	s_addc_u32 s31, s31, 0
	s_add_u32 s87, s34, 0x100
	v_mov_b32_e32 v0, 0
	s_addc_u32 s88, s35, 0
	s_mov_b32 s34, 0
	v_mov_b32_e32 v1, v0
	v_mov_b32_e32 v2, v0
	v_mov_b32_e32 v3, v0
	v_mov_b32_e32 v4, v0
	v_mov_b32_e32 v5, v0
	v_mov_b32_e32 v6, v0
	v_mov_b32_e32 v7, v0
	v_mov_b32_e32 v8, v0
	v_mov_b32_e32 v9, v0
	v_mov_b32_e32 v10, v0
	v_mov_b32_e32 v11, v0
	v_mov_b32_e32 v12, v0
	v_mov_b32_e32 v13, v0
	v_mov_b32_e32 v14, v0
	v_mov_b32_e32 v15, v0
	v_mov_b32_e32 v16, v0
	v_mov_b32_e32 v17, v0
	v_mov_b32_e32 v18, v0
	v_mov_b32_e32 v19, v0
	v_mov_b32_e32 v20, v0
	v_mov_b32_e32 v21, v0
	v_mov_b32_e32 v22, v0
	v_mov_b32_e32 v23, v0
	v_mov_b32_e32 v32, v0
	s_waitcnt lgkmcnt(0)
	v_mov_b32_e32 v33, v0
	v_mov_b32_e32 v34, v0
	v_mov_b32_e32 v35, v0
	v_mov_b32_e32 v36, v0
	v_mov_b32_e32 v37, v0
	v_mov_b32_e32 v38, v0
	v_mov_b32_e32 v39, v0
	v_mov_b32_e32 v24, v0
	v_mov_b32_e32 v25, v0
	v_mov_b32_e32 v26, v0
	v_mov_b32_e32 v27, v0
	v_mov_b32_e32 v28, v0
	v_mov_b32_e32 v29, v0
	v_mov_b32_e32 v30, v0
	v_mov_b32_e32 v31, v0
	v_mov_b32_e32 v40, v0
	v_mov_b32_e32 v41, v0
	v_mov_b32_e32 v42, v0
	v_mov_b32_e32 v43, v0
	v_mov_b32_e32 v44, v0
	v_mov_b32_e32 v45, v0
	v_mov_b32_e32 v46, v0
	v_mov_b32_e32 v47, v0
	v_mov_b32_e32 v48, v0
	v_mov_b32_e32 v49, v0
	v_mov_b32_e32 v50, v0
	v_mov_b32_e32 v51, v0
	v_mov_b32_e32 v52, v0
	v_mov_b32_e32 v53, v0
	v_mov_b32_e32 v54, v0
	v_mov_b32_e32 v55, v0
	v_mov_b32_e32 v56, v0
	v_mov_b32_e32 v57, v0
	v_mov_b32_e32 v58, v0
	v_mov_b32_e32 v59, v0
	v_mov_b32_e32 v60, v0
	v_mov_b32_e32 v61, v0
	v_mov_b32_e32 v62, v0
	v_mov_b32_e32 v63, v0
	v_mov_b32_e32 v64, v0
	v_mov_b32_e32 v65, v0
	v_mov_b32_e32 v66, v0
	v_mov_b32_e32 v67, v0
	v_mov_b32_e32 v68, v0
	v_mov_b32_e32 v69, v0
	v_mov_b32_e32 v70, v0
	v_mov_b32_e32 v71, v0
	v_mov_b32_e32 v72, v0
	v_mov_b32_e32 v73, v0
	v_mov_b32_e32 v74, v0
	v_mov_b32_e32 v75, v0
	v_mov_b32_e32 v76, v0
	v_mov_b32_e32 v77, v0
	v_mov_b32_e32 v78, v0
	v_mov_b32_e32 v79, v0
	v_mov_b32_e32 v80, v0
	v_mov_b32_e32 v81, v0
	v_mov_b32_e32 v82, v0
	v_mov_b32_e32 v83, v0
	v_mov_b32_e32 v84, v0
	v_mov_b32_e32 v85, v0
	v_mov_b32_e32 v86, v0
	v_mov_b32_e32 v87, v0
	v_mov_b32_e32 v96, v0
	v_mov_b32_e32 v97, v0
	v_mov_b32_e32 v98, v0
	v_mov_b32_e32 v99, v0
	v_mov_b32_e32 v100, v0
	v_mov_b32_e32 v101, v0
	v_mov_b32_e32 v102, v0
	v_mov_b32_e32 v103, v0
	v_mov_b32_e32 v88, v0
	v_mov_b32_e32 v89, v0
	v_mov_b32_e32 v90, v0
	v_mov_b32_e32 v91, v0
	v_mov_b32_e32 v92, v0
	v_mov_b32_e32 v93, v0
	v_mov_b32_e32 v94, v0
	v_mov_b32_e32 v95, v0
	v_mov_b32_e32 v104, v0
	v_mov_b32_e32 v105, v0
	v_mov_b32_e32 v106, v0
	v_mov_b32_e32 v107, v0
	v_mov_b32_e32 v108, v0
	v_mov_b32_e32 v109, v0
	v_mov_b32_e32 v110, v0
	v_mov_b32_e32 v111, v0
	v_mov_b32_e32 v112, v0
	v_mov_b32_e32 v113, v0
	v_mov_b32_e32 v114, v0
	v_mov_b32_e32 v115, v0
	v_mov_b32_e32 v116, v0
	v_mov_b32_e32 v117, v0
	v_mov_b32_e32 v118, v0
	v_mov_b32_e32 v119, v0
	v_mov_b32_e32 v120, v0
	v_mov_b32_e32 v121, v0
	v_mov_b32_e32 v122, v0
	v_mov_b32_e32 v123, v0
	v_mov_b32_e32 v124, v0
	v_mov_b32_e32 v125, v0
	v_mov_b32_e32 v126, v0
	v_mov_b32_e32 v127, v0
	.p2align	6

;     __device__ __forceinline__ bool next(int i, Unit& u) const {
;     ...
;         const long L = sk ? (long)nfull * G + (long)(ip - nfull) * (G - skew) + (c - skew) : (long)ip * G + c; const bool ok = L < nwg && (!sk || c >= skew);
;         int wgid = ok ? (int)L : 0; { const int q = nwg / NXCD, r = nwg % NXCD, xcd = wgid % NXCD, off = wgid / NXCD; wgid = (xcd < r ? xcd * (q + 1) : r * (q + 1) + (xcd - r) * q) + off; }
;         const int nig = WGM * nN, gid = wgid / nig, fm = gid * WGM, gsz = (nM - fm) < WGM ? (nM - fm) : WGM;
;         const int fpm = fm + ((wgid % nig) % gsz), fpn = (wgid % nig) / gsz;
;         const int ns = nsplit > 0 ? nsplit : 1, t = c / ns, ks = c - t * ns, mpm = mini_pm0 + t / nN, mpn = t % nN;
;         u.pm = __builtin_amdgcn_readfirstlane(mini ? mpm : fpm); u.pn = __builtin_amdgcn_readfirstlane(mini ? mpn : fpn);
;         const int kh = mini_pair ? ns / 2 : ns, msub = mini_pair ? ks / kh : 0, mk = ks - msub * kh;
;         u.sub = __builtin_amdgcn_readfirstlane(mini ? msub : (j & ((1 << pair) - 1))); u.kt0 = __builtin_amdgcn_readfirstlane(mini ? mk * mini_nkt : 0); u.nkt = mini ? mini_nkt : nkt_full; u.part = mini ? 1 + ks : 0;
.LBB0_2057:
	s_add_i32 s11, s16, s29
	s_ashr_i32 s16, s11, 31
	s_lshr_b32 s16, s16, 27
	s_add_i32 s16, s11, s16
	s_ashr_i32 s29, s16, 5
	s_lshl_b32 s29, s29, 2
	s_sub_i32 s30, 0x80, s29
	s_min_i32 s31, s30, 4
	s_abs_i32 s30, s31
	v_cvt_f32_u32_e32 v128, s30
	s_sub_i32 s35, 0, s30
	s_andn2_b32 s16, s16, 31
	s_sub_i32 s11, s11, s16
	v_rcp_iflag_f32_e32 v128, v128
	s_abs_i32 s16, s11
	s_xor_b32 s34, s11, s31
	s_ashr_i32 s34, s34, 31
	v_mul_f32_e32 v128, 0x4f7ffffe, v128
	v_cvt_u32_f32_e32 v128, v128
	s_mov_b32 s42, 0
	v_readfirstlane_b32 s36, v128
	s_mul_i32 s35, s35, s36
	s_mul_hi_u32 s35, s36, s35
	s_add_i32 s36, s36, s35
	s_mul_hi_u32 s35, s16, s36
	s_mul_i32 s36, s35, s30
	s_sub_i32 s16, s16, s36
	s_add_i32 s37, s35, 1
	s_sub_i32 s36, s16, s30
	s_cmp_ge_u32 s16, s30
	s_cselect_b32 s35, s37, s35
	s_cselect_b32 s16, s36, s16
	s_add_i32 s36, s35, 1
	s_cmp_ge_u32 s16, s30
	s_cselect_b32 s16, s36, s35
	s_xor_b32 s16, s16, s34
	s_sub_i32 s30, s16, s34
	s_mul_i32 s16, s30, s31
	s_sub_i32 s11, s11, s16
	s_add_i32 s34, s29, s11
	s_ashr_i32 s35, s34, 31
	s_and_b32 s49, s3, 1
	s_lshl_b64 s[36:37], s[34:35], 18
	s_cmp_eq_u32 s49, 0
	s_cselect_b32 s11, s56, s51
	s_cselect_b32 s3, s57, s53
	s_cselect_b32 s29, s27, s55
	s_cselect_b32 s35, s50, s70
	s_add_u32 s36, s11, s36
	s_addc_u32 s37, s3, s37
	s_and_b64 s[38:39], s[6:7], exec
	s_cselect_b32 s11, s37, s65
	s_cselect_b32 s16, s36, s64
	s_ashr_i32 s31, s30, 31
	s_lshl_b64 s[38:39], s[30:31], 18
	s_add_u32 s38, s29, s38
	s_addc_u32 s39, s35, s39
	s_and_b64 s[68:69], s[6:7], exec
	s_cselect_b32 s29, s39, s67
	s_cselect_b32 s31, s38, s66
	s_add_i32 s35, s9, -2
	s_add_u32 s64, s64, 0x20080
	s_addc_u32 s65, s65, 0
	s_add_u32 s89, s66, 0x100
	s_addc_u32 s90, s67, 0
	.p2align	6

;     __device__ __forceinline__ bool next(int i, Unit& u) const {
;     ...
;         int wgid = ok ? (int)L : 0; { const int q = nwg / NXCD, r = nwg % NXCD, xcd = wgid % NXCD, off = wgid / NXCD; wgid = (xcd < r ? xcd * (q + 1) : r * (q + 1) + (xcd - r) * q) + off; }
;         const int nig = WGM * nN, gid = wgid / nig, fm = gid * WGM, gsz = (nM - fm) < WGM ? (nM - fm) : WGM;
;         const int fpm = fm + ((wgid % nig) % gsz), fpn = (wgid % nig) / gsz;
;         const int ns = nsplit > 0 ? nsplit : 1, t = c / ns, ks = c - t * ns, mpm = mini_pm0 + t / nN, mpn = t % nN;
;         u.pm = __builtin_amdgcn_readfirstlane(mini ? mpm : fpm); u.pn = __builtin_amdgcn_readfirstlane(mini ? mpn : fpn);
; template <class Epi, bool ALIGN_EPI = true, bool FP8 = false>
; __device__ __forceinline__ void gemm_phase(LAS unsigned char* lds, const Gemm g, const StaticOrder& S, const Epi& E, const int wid) {
;     ...
; #pragma unroll
;         for (int a = 0; a < 2; ++a)
; #pragma unroll
;             for (int b = 0; b < 2; ++b)
; #pragma unroll
;                 for (int m = 0; m < 4; ++m) {
;                     if (!keep) { acc[a][b][m][0] = (f32x4){0.f, 0.f, 0.f, 0.f}; acc[a][b][m][1] = (f32x4){0.f, 0.f, 0.f, 0.f}; }
;                     if constexpr (FP8) acc8[a][b][m] = __builtin_shufflevector(acc[a][b][m][0], acc[a][b][m][1], 0, 1, 2, 3, 4, 5, 6, 7); }
.LBB0_2289:
	s_ashr_i32 s3, s3, 3
	s_add_i32 s3, s21, s3
	s_ashr_i32 s18, s3, 31
	s_lshr_b32 s18, s18, 27
	s_add_i32 s18, s3, s18
	s_ashr_i32 s19, s18, 5
	s_lshl_b32 s19, s19, 2
	s_sub_i32 s20, 0x80, s19
	s_min_i32 s20, s20, 4
	s_abs_i32 s21, s20
	v_cvt_f32_u32_e32 v0, s21
	s_sub_i32 s23, 0, s21
	s_andn2_b32 s18, s18, 31
	s_sub_i32 s3, s3, s18
	v_rcp_iflag_f32_e32 v0, v0
	s_abs_i32 s18, s3
	s_xor_b32 s22, s3, s20
	s_ashr_i32 s22, s22, 31
	v_mul_f32_e32 v0, 0x4f7ffffe, v0
	v_cvt_u32_f32_e32 v0, v0
	s_mov_b32 s38, 0
	v_readfirstlane_b32 s24, v0
	s_mul_i32 s23, s23, s24
	s_mul_hi_u32 s23, s24, s23
	s_add_i32 s24, s24, s23
	s_mul_hi_u32 s23, s18, s24
	s_mul_i32 s24, s23, s21
	s_sub_i32 s18, s18, s24
	s_add_i32 s25, s23, 1
	s_sub_i32 s24, s18, s21
	s_cmp_ge_u32 s18, s21
	s_cselect_b32 s23, s25, s23
	s_cselect_b32 s18, s24, s18
	s_add_i32 s24, s23, 1
	s_cmp_ge_u32 s18, s21
	s_cselect_b32 s18, s24, s23
	s_xor_b32 s18, s18, s22
	s_sub_i32 s18, s18, s22
	s_mul_i32 s20, s18, s20
	s_sub_i32 s3, s3, s20
	s_add_i32 s20, s19, s3
	s_ashr_i32 s21, s20, 31
	s_lshl_b64 s[22:23], s[20:21], 19
	s_add_u32 s22, s48, s22
	s_addc_u32 s23, s49, s23
	s_and_b64 s[24:25], s[4:5], exec
	s_cselect_b32 s21, s23, s35
	s_cselect_b32 s31, s22, s34
	s_ashr_i32 s19, s18, 31
	s_lshl_b64 s[24:25], s[18:19], 19
	s_add_u32 s24, s50, s24
	s_addc_u32 s25, s51, s25
	s_and_b64 s[42:43], s[4:5], exec
	s_cselect_b32 s19, s25, s37
	s_cselect_b32 s87, s24, s36
	s_add_i32 s88, s29, -2
	s_add_u32 s34, s34, 0x40080
	s_addc_u32 s35, s35, 0
	s_add_u32 s89, s36, 0x100
	v_mov_b32_e32 v0, 0
	s_addc_u32 s90, s37, 0
	v_mov_b32_e32 v1, v0
	v_mov_b32_e32 v2, v0
	v_mov_b32_e32 v3, v0
	v_mov_b32_e32 v4, v0
	v_mov_b32_e32 v5, v0
	v_mov_b32_e32 v6, v0
	v_mov_b32_e32 v7, v0
	v_mov_b32_e32 v8, v0
	v_mov_b32_e32 v9, v0
	v_mov_b32_e32 v10, v0
	v_mov_b32_e32 v11, v0
	v_mov_b32_e32 v12, v0
	v_mov_b32_e32 v13, v0
	v_mov_b32_e32 v14, v0
	v_mov_b32_e32 v15, v0
	v_mov_b32_e32 v24, v0
	v_mov_b32_e32 v25, v0
	v_mov_b32_e32 v26, v0
	v_mov_b32_e32 v27, v0
	v_mov_b32_e32 v28, v0
	v_mov_b32_e32 v29, v0
	v_mov_b32_e32 v30, v0
	v_mov_b32_e32 v31, v0
	v_mov_b32_e32 v40, v0
	v_mov_b32_e32 v41, v0
	v_mov_b32_e32 v42, v0
	v_mov_b32_e32 v43, v0
	v_mov_b32_e32 v44, v0
	v_mov_b32_e32 v45, v0
	v_mov_b32_e32 v46, v0
	v_mov_b32_e32 v47, v0
	v_mov_b32_e32 v16, v0
	v_mov_b32_e32 v17, v0
	v_mov_b32_e32 v18, v0
	v_mov_b32_e32 v19, v0
	v_mov_b32_e32 v20, v0
	v_mov_b32_e32 v21, v0
	v_mov_b32_e32 v22, v0
	v_mov_b32_e32 v23, v0
	v_mov_b32_e32 v32, v0
	s_waitcnt lgkmcnt(0)
	v_mov_b32_e32 v33, v0
	v_mov_b32_e32 v34, v0
	v_mov_b32_e32 v35, v0
	v_mov_b32_e32 v36, v0
	v_mov_b32_e32 v37, v0
	v_mov_b32_e32 v38, v0
	v_mov_b32_e32 v39, v0
	v_mov_b32_e32 v48, v0
	v_mov_b32_e32 v49, v0
	v_mov_b32_e32 v50, v0
	v_mov_b32_e32 v51, v0
	v_mov_b32_e32 v52, v0
	v_mov_b32_e32 v53, v0
	v_mov_b32_e32 v54, v0
	v_mov_b32_e32 v55, v0
	v_mov_b32_e32 v56, v0
	v_mov_b32_e32 v57, v0
	v_mov_b32_e32 v58, v0
	v_mov_b32_e32 v59, v0
	v_mov_b32_e32 v60, v0
	v_mov_b32_e32 v61, v0
	v_mov_b32_e32 v62, v0
	v_mov_b32_e32 v63, v0
	v_mov_b32_e32 v64, v0
	v_mov_b32_e32 v65, v0
	v_mov_b32_e32 v66, v0
	v_mov_b32_e32 v67, v0
	v_mov_b32_e32 v68, v0
	v_mov_b32_e32 v69, v0
	v_mov_b32_e32 v70, v0
	v_mov_b32_e32 v71, v0
	v_mov_b32_e32 v72, v0
	v_mov_b32_e32 v73, v0
	v_mov_b32_e32 v74, v0
	v_mov_b32_e32 v75, v0
	v_mov_b32_e32 v76, v0
	v_mov_b32_e32 v77, v0
	v_mov_b32_e32 v78, v0
	v_mov_b32_e32 v79, v0
	v_mov_b32_e32 v88, v0
	v_mov_b32_e32 v89, v0
	v_mov_b32_e32 v90, v0
	v_mov_b32_e32 v91, v0
	v_mov_b32_e32 v92, v0
	v_mov_b32_e32 v93, v0
	v_mov_b32_e32 v94, v0
	v_mov_b32_e32 v95, v0
	v_mov_b32_e32 v112, v0
	v_mov_b32_e32 v113, v0
	v_mov_b32_e32 v114, v0
	v_mov_b32_e32 v115, v0
	v_mov_b32_e32 v116, v0
	v_mov_b32_e32 v117, v0
	v_mov_b32_e32 v118, v0
	v_mov_b32_e32 v119, v0
	v_mov_b32_e32 v80, v0
	v_mov_b32_e32 v81, v0
	v_mov_b32_e32 v82, v0
	v_mov_b32_e32 v83, v0
	v_mov_b32_e32 v84, v0
	v_mov_b32_e32 v85, v0
	v_mov_b32_e32 v86, v0
	v_mov_b32_e32 v87, v0
	v_mov_b32_e32 v96, v0
	v_mov_b32_e32 v97, v0
	v_mov_b32_e32 v98, v0
	v_mov_b32_e32 v99, v0
	v_mov_b32_e32 v100, v0
	v_mov_b32_e32 v101, v0
	v_mov_b32_e32 v102, v0
	v_mov_b32_e32 v103, v0
	v_mov_b32_e32 v104, v0
	v_mov_b32_e32 v105, v0
	v_mov_b32_e32 v106, v0
	v_mov_b32_e32 v107, v0
	v_mov_b32_e32 v108, v0
	v_mov_b32_e32 v109, v0
	v_mov_b32_e32 v110, v0
	v_mov_b32_e32 v111, v0
	v_mov_b32_e32 v120, v0
	v_mov_b32_e32 v121, v0
	v_mov_b32_e32 v122, v0
	v_mov_b32_e32 v123, v0
	v_mov_b32_e32 v124, v0
	v_mov_b32_e32 v125, v0
	v_mov_b32_e32 v126, v0
	v_mov_b32_e32 v127, v0
	s_waitcnt vmcnt(0)
	.p2align	6

;     __device__ __forceinline__ bool next(int i, Unit& u) const {
;         const bool hm = c < nmini, mini = hm && i == 0;
;         int j = i - (hm ? 1 : 0); j = j < 0 ? 0 : j;
;         const int ip = j >> pair;
;         const bool sk = skew > 0 && ip >= nfull;
;         const long L = sk ? (long)nfull * G + (long)(ip - nfull) * (G - skew) + (c - skew) : (long)ip * G + c; const bool ok = L < nwg && (!sk || c >= skew);
;         int wgid = ok ? (int)L : 0; { const int q = nwg / NXCD, r = nwg % NXCD, xcd = wgid % NXCD, off = wgid / NXCD; wgid = (xcd < r ? xcd * (q + 1) : r * (q + 1) + (xcd - r) * q) + off; }
;         const int nig = WGM * nN, gid = wgid / nig, fm = gid * WGM, gsz = (nM - fm) < WGM ? (nM - fm) : WGM;
;         const int fpm = fm + ((wgid % nig) % gsz), fpn = (wgid % nig) / gsz;
;         const int ns = nsplit > 0 ? nsplit : 1, t = c / ns, ks = c - t * ns, mpm = mini_pm0 + t / nN, mpn = t % nN;
;         u.pm = __builtin_amdgcn_readfirstlane(mini ? mpm : fpm); u.pn = __builtin_amdgcn_readfirstlane(mini ? mpn : fpn);
; template <class Epi, bool ALIGN_EPI = true, bool FP8 = false>
; __device__ __forceinline__ void gemm_phase(LAS unsigned char* lds, const Gemm g, const StaticOrder& S, const Epi& E, const int wid) {
;     ...
; #pragma unroll
;         for (int a = 0; a < 2; ++a)
; #pragma unroll
;             for (int b = 0; b < 2; ++b)
; #pragma unroll
;                 for (int m = 0; m < 4; ++m) {
;                     if (!keep) { acc[a][b][m][0] = (f32x4){0.f, 0.f, 0.f, 0.f}; acc[a][b][m][1] = (f32x4){0.f, 0.f, 0.f, 0.f}; }
;                     if constexpr (FP8) acc8[a][b][m] = __builtin_shufflevector(acc[a][b][m][0], acc[a][b][m][1], 0, 1, 2, 3, 4, 5, 6, 7); }
.LBB0_2450:
	s_add_i32 s74, s74, 1
	s_add_i32 s3, s74, s50
	s_mul_i32 s4, s3, s51
	s_mul_hi_u32 s5, s3, s33
	s_add_i32 s5, s5, s4
	s_mul_i32 s3, s3, s33
	s_add_u32 s16, s3, s2
	s_addc_u32 s17, s5, s50
	v_cmp_lt_i64_e64 s[4:5], s[16:17], v[142:143]
	s_and_b64 s[18:19], s[4:5], exec
	s_cselect_b32 s3, s16, 0
	s_ashr_i32 s16, s3, 31
	s_lshr_b32 s16, s16, 29
	s_add_i32 s16, s3, s16
	s_ashr_i32 s17, s16, 3
	s_and_b32 s16, s16, -8
	s_sub_i32 s3, s3, s16
	s_cmp_lt_i32 s3, 0
	s_cselect_b32 s16, s64, 0x2cb
	s_mul_i32 s3, s3, s16
	s_add_i32 s3, s3, s17
	s_mul_hi_i32 s16, s3, 0x2e8ba2e9
	s_lshr_b32 s17, s16, 31
	s_ashr_i32 s16, s16, 5
	s_add_i32 s16, s16, s17
	s_lshl_b32 s17, s16, 2
	s_sub_i32 s18, 0x82, s17
	s_min_i32 s18, s18, 4
	s_abs_i32 s19, s18
	v_cvt_f32_u32_e32 v0, s19
	s_sub_i32 s21, 0, s19
	s_mulk_i32 s16, 0xb0
	s_sub_i32 s3, s3, s16
	v_rcp_iflag_f32_e32 v0, v0
	s_abs_i32 s20, s3
	s_xor_b32 s16, s3, s18
	s_ashr_i32 s16, s16, 31
	v_mul_f32_e32 v0, 0x4f7ffffe, v0
	v_cvt_u32_f32_e32 v0, v0
	s_nop 0
	v_readfirstlane_b32 s22, v0
	s_mul_i32 s21, s21, s22
	s_mul_hi_u32 s21, s22, s21
	s_add_i32 s22, s22, s21
	s_mul_hi_u32 s21, s20, s22
	s_mul_i32 s22, s21, s19
	s_sub_i32 s20, s20, s22
	s_add_i32 s22, s21, 1
	s_sub_i32 s23, s20, s19
	s_cmp_ge_u32 s20, s19
	s_cselect_b32 s21, s22, s21
	s_cselect_b32 s20, s23, s20
	s_add_i32 s22, s21, 1
	s_cmp_ge_u32 s20, s19
	s_cselect_b32 s19, s22, s21
	s_xor_b32 s19, s19, s16
	s_sub_i32 s16, s19, s16
	s_mul_i32 s18, s16, s18
	s_sub_i32 s3, s3, s18
	s_add_i32 s18, s17, s3
	s_ashr_i32 s19, s18, 31
	s_lshl_b64 s[20:21], s[18:19], 20
	s_add_u32 s20, s56, s20
	s_addc_u32 s21, s57, s21
	s_ashr_i32 s17, s16, 31
	s_lshl_b64 s[22:23], s[16:17], 20
	s_add_u32 s22, s36, s22
	s_addc_u32 s23, s37, s23
	s_cmp_eq_u32 s54, 0
	s_cbranch_scc1 .LBB0_2458
	s_and_b64 s[34:35], s[4:5], exec
	s_cselect_b32 s3, s21, s29
	s_cselect_b32 s17, s20, s28
	s_cselect_b32 s19, s23, s31
	s_cselect_b32 s42, s22, s30
	s_add_i32 s43, s54, -2
	s_add_u32 s28, s28, 0x80080
	s_addc_u32 s29, s29, 0
	s_add_u32 s52, s30, 0x100
	v_mov_b32_e32 v0, 0
	s_addc_u32 s75, s31, 0
	s_mov_b32 s30, 0
	v_mov_b32_e32 v1, v0
	v_mov_b32_e32 v2, v0
	v_mov_b32_e32 v3, v0
	v_mov_b32_e32 v8, v0
	v_mov_b32_e32 v9, v0
	v_mov_b32_e32 v10, v0
	v_mov_b32_e32 v11, v0
	v_mov_b32_e32 v16, v0
	v_mov_b32_e32 v17, v0
	v_mov_b32_e32 v18, v0
	v_mov_b32_e32 v19, v0
	v_mov_b32_e32 v24, v0
	v_mov_b32_e32 v25, v0
	v_mov_b32_e32 v26, v0
	v_mov_b32_e32 v27, v0
	v_mov_b32_e32 v32, v0
	s_waitcnt lgkmcnt(0)
	v_mov_b32_e32 v33, v0
	v_mov_b32_e32 v34, v0
	v_mov_b32_e32 v35, v0
	v_mov_b32_e32 v40, v0
	v_mov_b32_e32 v41, v0
	v_mov_b32_e32 v42, v0
	v_mov_b32_e32 v43, v0
	v_mov_b32_e32 v48, v0
	v_mov_b32_e32 v49, v0
	v_mov_b32_e32 v50, v0
	v_mov_b32_e32 v51, v0
	v_mov_b32_e32 v56, v0
	v_mov_b32_e32 v57, v0
	v_mov_b32_e32 v58, v0
	v_mov_b32_e32 v59, v0
	v_mov_b32_e32 v4, v0
	v_mov_b32_e32 v5, v0
	v_mov_b32_e32 v6, v0
	v_mov_b32_e32 v7, v0
	v_mov_b32_e32 v12, v0
	v_mov_b32_e32 v13, v0
	v_mov_b32_e32 v14, v0
	v_mov_b32_e32 v15, v0
	v_mov_b32_e32 v20, v0
	v_mov_b32_e32 v21, v0
	v_mov_b32_e32 v22, v0
	v_mov_b32_e32 v23, v0
	v_mov_b32_e32 v28, v0
	v_mov_b32_e32 v29, v0
	v_mov_b32_e32 v30, v0
	v_mov_b32_e32 v31, v0
	v_mov_b32_e32 v36, v0
	v_mov_b32_e32 v37, v0
	v_mov_b32_e32 v38, v0
	v_mov_b32_e32 v39, v0
	v_mov_b32_e32 v44, v0
	v_mov_b32_e32 v45, v0
	v_mov_b32_e32 v46, v0
	v_mov_b32_e32 v47, v0
	v_mov_b32_e32 v52, v0
	v_mov_b32_e32 v53, v0
	v_mov_b32_e32 v54, v0
	v_mov_b32_e32 v55, v0
	v_mov_b32_e32 v60, v0
	v_mov_b32_e32 v61, v0
	v_mov_b32_e32 v62, v0
	v_mov_b32_e32 v63, v0
	v_mov_b32_e32 v64, v0
	v_mov_b32_e32 v65, v0
	v_mov_b32_e32 v66, v0
	v_mov_b32_e32 v67, v0
	v_mov_b32_e32 v72, v0
	v_mov_b32_e32 v73, v0
	v_mov_b32_e32 v74, v0
	v_mov_b32_e32 v75, v0
	v_mov_b32_e32 v80, v0
	v_mov_b32_e32 v81, v0
	v_mov_b32_e32 v82, v0
	v_mov_b32_e32 v83, v0
	v_mov_b32_e32 v88, v0
	v_mov_b32_e32 v89, v0
	v_mov_b32_e32 v90, v0
	v_mov_b32_e32 v91, v0
	v_mov_b32_e32 v96, v0
	v_mov_b32_e32 v97, v0
	v_mov_b32_e32 v98, v0
	v_mov_b32_e32 v99, v0
	v_mov_b32_e32 v104, v0
	v_mov_b32_e32 v105, v0
	v_mov_b32_e32 v106, v0
	v_mov_b32_e32 v107, v0
	v_mov_b32_e32 v112, v0
	v_mov_b32_e32 v113, v0
	v_mov_b32_e32 v114, v0
	v_mov_b32_e32 v115, v0
	v_mov_b32_e32 v120, v0
	v_mov_b32_e32 v121, v0
	v_mov_b32_e32 v122, v0
	v_mov_b32_e32 v123, v0
	v_mov_b32_e32 v68, v0
	v_mov_b32_e32 v69, v0
	v_mov_b32_e32 v70, v0
	v_mov_b32_e32 v71, v0
	v_mov_b32_e32 v76, v0
	v_mov_b32_e32 v77, v0
	v_mov_b32_e32 v78, v0
	v_mov_b32_e32 v79, v0
	v_mov_b32_e32 v84, v0
	v_mov_b32_e32 v85, v0
	v_mov_b32_e32 v86, v0
	v_mov_b32_e32 v87, v0
	v_mov_b32_e32 v92, v0
	v_mov_b32_e32 v93, v0
	v_mov_b32_e32 v94, v0
	v_mov_b32_e32 v95, v0
	v_mov_b32_e32 v100, v0
	v_mov_b32_e32 v101, v0
	v_mov_b32_e32 v102, v0
	v_mov_b32_e32 v103, v0
	v_mov_b32_e32 v108, v0
	v_mov_b32_e32 v109, v0
	v_mov_b32_e32 v110, v0
	v_mov_b32_e32 v111, v0
	v_mov_b32_e32 v116, v0
	v_mov_b32_e32 v117, v0
	v_mov_b32_e32 v118, v0
	v_mov_b32_e32 v119, v0
	v_mov_b32_e32 v124, v0
	v_mov_b32_e32 v125, v0
	v_mov_b32_e32 v126, v0
	v_mov_b32_e32 v127, v0
	.p2align	6

; template <class Epi, bool ALIGN_EPI = true, bool FP8 = false>
; __device__ __forceinline__ void gemm_phase(LAS unsigned char* lds, const Gemm g, const StaticOrder& S, const Epi& E, const int wid) {
;     ...
;         const int nt = cur.nkt;
;         for (int t = 0; t < nt; t += 2) {
;             const bool last = (t == nt - 2);
;             if constexpr (FP8) {
; #pragma unroll
;                 for (int a = 0; a < 2; ++a)
; #pragma unroll
;                     for (int b = 0; b < 2; ++b)
; #pragma unroll
;                         for (int m = 0; m < 4; ++m) asm volatile("" : "+v"(acc8[a][b][m]));
;             }
;             const char* a1 = cA + (size_t)(t + 1) * kstep;
;             const char* a2 = last ? nA : cA + (size_t)(t + 2) * kstep; const char* b2 = last ? nB : cB + (size_t)(t + 2) * kstep;
;     ...
; #pragma unroll
;         for (int a = 0; a < 2; ++a)
; #pragma unroll
;             for (int b = 0; b < 2; ++b)
; #pragma unroll
;                 for (int m = 0; m < 4; ++m) {
;                     if (!keep) { acc[a][b][m][0] = (f32x4){0.f, 0.f, 0.f, 0.f}; acc[a][b][m][1] = (f32x4){0.f, 0.f, 0.f, 0.f}; }
;                     if constexpr (FP8) acc8[a][b][m] = __builtin_shufflevector(acc[a][b][m][0], acc[a][b][m][1], 0, 1, 2, 3, 4, 5, 6, 7); }
.LBB0_2535:
	s_add_i32 s81, s80, -2
	s_add_u32 s24, s24, 0xb0080
	s_addc_u32 s25, s25, 0
	s_add_u32 s82, s26, 0x100
	v_mov_b32_e32 v0, 0
	s_addc_u32 s83, s27, 0
	s_mov_b32 s26, 0
	v_mov_b32_e32 v1, v0
	v_mov_b32_e32 v2, v0
	v_mov_b32_e32 v3, v0
	v_mov_b32_e32 v4, v0
	v_mov_b32_e32 v5, v0
	v_mov_b32_e32 v6, v0
	v_mov_b32_e32 v7, v0
	v_mov_b32_e32 v8, v0
	v_mov_b32_e32 v9, v0
	v_mov_b32_e32 v10, v0
	v_mov_b32_e32 v11, v0
	v_mov_b32_e32 v12, v0
	v_mov_b32_e32 v13, v0
	v_mov_b32_e32 v14, v0
	v_mov_b32_e32 v15, v0
	v_mov_b32_e32 v24, v0
	v_mov_b32_e32 v25, v0
	v_mov_b32_e32 v26, v0
	v_mov_b32_e32 v27, v0
	v_mov_b32_e32 v28, v0
	v_mov_b32_e32 v29, v0
	v_mov_b32_e32 v30, v0
	v_mov_b32_e32 v31, v0
	v_mov_b32_e32 v40, v0
	v_mov_b32_e32 v41, v0
	v_mov_b32_e32 v42, v0
	v_mov_b32_e32 v43, v0
	v_mov_b32_e32 v44, v0
	v_mov_b32_e32 v45, v0
	v_mov_b32_e32 v46, v0
	v_mov_b32_e32 v47, v0
	v_mov_b32_e32 v16, v0
	v_mov_b32_e32 v17, v0
	v_mov_b32_e32 v18, v0
	v_mov_b32_e32 v19, v0
	v_mov_b32_e32 v20, v0
	v_mov_b32_e32 v21, v0
	v_mov_b32_e32 v22, v0
	v_mov_b32_e32 v23, v0
	v_mov_b32_e32 v32, v0
	s_waitcnt lgkmcnt(0)
	v_mov_b32_e32 v33, v0
	v_mov_b32_e32 v34, v0
	v_mov_b32_e32 v35, v0
	v_mov_b32_e32 v36, v0
	v_mov_b32_e32 v37, v0
	v_mov_b32_e32 v38, v0
	v_mov_b32_e32 v39, v0
	v_mov_b32_e32 v48, v0
	v_mov_b32_e32 v49, v0
	v_mov_b32_e32 v50, v0
	v_mov_b32_e32 v51, v0
	v_mov_b32_e32 v52, v0
	v_mov_b32_e32 v53, v0
	v_mov_b32_e32 v54, v0
	v_mov_b32_e32 v55, v0
	v_mov_b32_e32 v56, v0
	v_mov_b32_e32 v57, v0
	v_mov_b32_e32 v58, v0
	v_mov_b32_e32 v59, v0
	v_mov_b32_e32 v60, v0
	v_mov_b32_e32 v61, v0
	v_mov_b32_e32 v62, v0
	v_mov_b32_e32 v63, v0
	v_mov_b32_e32 v64, v0
	v_mov_b32_e32 v65, v0
	v_mov_b32_e32 v66, v0
	v_mov_b32_e32 v67, v0
	v_mov_b32_e32 v68, v0
	v_mov_b32_e32 v69, v0
	v_mov_b32_e32 v70, v0
	v_mov_b32_e32 v71, v0
	v_mov_b32_e32 v72, v0
	v_mov_b32_e32 v73, v0
	v_mov_b32_e32 v74, v0
	v_mov_b32_e32 v75, v0
	v_mov_b32_e32 v76, v0
	v_mov_b32_e32 v77, v0
	v_mov_b32_e32 v78, v0
	v_mov_b32_e32 v79, v0
	v_mov_b32_e32 v88, v0
	v_mov_b32_e32 v89, v0
	v_mov_b32_e32 v90, v0
	v_mov_b32_e32 v91, v0
	v_mov_b32_e32 v92, v0
	v_mov_b32_e32 v93, v0
	v_mov_b32_e32 v94, v0
	v_mov_b32_e32 v95, v0
	v_mov_b32_e32 v104, v0
	v_mov_b32_e32 v105, v0
	v_mov_b32_e32 v106, v0
	v_mov_b32_e32 v107, v0
	v_mov_b32_e32 v108, v0
	v_mov_b32_e32 v109, v0
	v_mov_b32_e32 v110, v0
	v_mov_b32_e32 v111, v0
	v_mov_b32_e32 v80, v0
	v_mov_b32_e32 v81, v0
	v_mov_b32_e32 v82, v0
	v_mov_b32_e32 v83, v0
	v_mov_b32_e32 v84, v0
	v_mov_b32_e32 v85, v0
	v_mov_b32_e32 v86, v0
	v_mov_b32_e32 v87, v0
	v_mov_b32_e32 v96, v0
	v_mov_b32_e32 v97, v0
	v_mov_b32_e32 v98, v0
	v_mov_b32_e32 v99, v0
	v_mov_b32_e32 v100, v0
	v_mov_b32_e32 v101, v0
	v_mov_b32_e32 v102, v0
	v_mov_b32_e32 v103, v0
	v_mov_b32_e32 v112, v0
	v_mov_b32_e32 v113, v0
	v_mov_b32_e32 v114, v0
	v_mov_b32_e32 v115, v0
	v_mov_b32_e32 v116, v0
	v_mov_b32_e32 v117, v0
	v_mov_b32_e32 v118, v0
	v_mov_b32_e32 v119, v0
	v_mov_b32_e32 v120, v0
	v_mov_b32_e32 v121, v0
	v_mov_b32_e32 v122, v0
	v_mov_b32_e32 v123, v0
	v_mov_b32_e32 v124, v0
	v_mov_b32_e32 v125, v0
	v_mov_b32_e32 v126, v0
	v_mov_b32_e32 v127, v0
	.p2align	6
